# conv fill phase rewritten: wave-uniform row index, all 16 a/gate row loads issued up front via saddr, single vmcnt wait, batched sigmoid-GLU (same f32 math) then LDS writes
# baseline (speedup 1.0000x reference)
; #define LAS __attribute__((address_space(3)))
; __device__ __forceinline__ float sigmoidf_(float x) { return __builtin_amdgcn_rcpf(1.0f + __builtin_amdgcn_exp2f(-x * LOG2E)); }
; __device__ __forceinline__ void conv_unit(const Ctx& C0, const Params& p, int l, int unit) {
;     ...
;     { const int cg8 = (c & 63) * 8, rsub = c >> 6;
; #pragma unroll
;       for (int pass = 0; pass < 8; ++pass) {
;         const int r = pass * 8 + rsub;
;         if (r < 62) {
;             const int s = s0 - 30 + r; f32x4 u0 = (f32x4){0.f, 0.f, 0.f, 0.f}, u1 = u0;
;             if (s >= 0) { const bf16* row = P + (size_t)(t0 - 30 + r) * PN + C_UB + cg8; const v4u a = *(const v4u*)row, g = *(const v4u*)(row + 512);
;                 u0[0] = bflo(a.x) * sigmoidf_(bflo(g.x)); u0[1] = bfhi(a.x) * sigmoidf_(bfhi(g.x)); u0[2] = bflo(a.y) * sigmoidf_(bflo(g.y)); u0[3] = bfhi(a.y) * sigmoidf_(bfhi(g.y));
;                 u1[0] = bflo(a.z) * sigmoidf_(bflo(g.z)); u1[1] = bfhi(a.z) * sigmoidf_(bfhi(g.z)); u1[2] = bflo(a.w) * sigmoidf_(bflo(g.w)); u1[3] = bfhi(a.w) * sigmoidf_(bfhi(g.w)); }
;             *(LAS f32x4*)(U + r * 512 + cg8) = u0; *(LAS f32x4*)(U + r * 512 + cg8 + 4) = u1;
;         }
;       }
.LBB0_280:
	v_mov_b32_e32 v10, v185
	s_lshl_b32 s0, s37, 5
	v_lshlrev_b32_e32 v0, 3, v10
	s_and_b32 s1, s0, 0xfe0
	v_and_b32_e32 v12, 0x1f8, v0
	v_ashrrev_i32_e32 v13, 6, v10
	v_lshl_add_u32 v11, v12, 2, 0
	s_sub_i32 s9, 29, s1
	s_sub_i32 s8, s0, 30
	v_readfirstlane_b32 s0, v13
	v_lshlrev_b32_e32 v0, 1, v12
	v_lshl_add_u32 v14, v13, 11, v11
	v_add_u32_e32 v15, 0x10000, v14
	s_add_i32 s1, s0, 0
	s_cmp_gt_i32 s1, s9
	s_cbranch_scc0 .Lcf_zero0
	s_add_i32 s10, s8, s1
	s_mul_i32 s10, s10, s86
	s_add_u32 s12, s18, s10
	s_addc_u32 s13, s19, 0
	s_add_u32 s12, s12, 0x6900600
	s_addc_u32 s13, s13, 0
	global_load_dwordx4 v[16:19], v0, s[12:13]
	global_load_dwordx4 v[20:23], v0, s[12:13] offset:1024
	s_branch .Lcf_next0
.Lcf_zero0:
	v_mov_b32_e32 v16, 0
	v_mov_b32_e32 v17, 0
	v_mov_b32_e32 v18, 0
	v_mov_b32_e32 v19, 0
	v_mov_b32_e32 v20, 0
	v_mov_b32_e32 v21, 0
	v_mov_b32_e32 v22, 0
	v_mov_b32_e32 v23, 0
.Lcf_next0:
	s_add_i32 s1, s0, 8
	s_cmp_gt_i32 s1, s9
	s_cbranch_scc0 .Lcf_zero1
	s_add_i32 s10, s8, s1
	s_mul_i32 s10, s10, s86
	s_add_u32 s20, s18, s10
	s_addc_u32 s21, s19, 0
	s_add_u32 s20, s20, 0x6900600
	s_addc_u32 s21, s21, 0
	global_load_dwordx4 v[24:27], v0, s[20:21]
	global_load_dwordx4 v[28:31], v0, s[20:21] offset:1024
	s_branch .Lcf_next1
.Lcf_zero1:
	v_mov_b32_e32 v24, 0
	v_mov_b32_e32 v25, 0
	v_mov_b32_e32 v26, 0
	v_mov_b32_e32 v27, 0
	v_mov_b32_e32 v28, 0
	v_mov_b32_e32 v29, 0
	v_mov_b32_e32 v30, 0
	v_mov_b32_e32 v31, 0
.Lcf_next1:
	s_add_i32 s1, s0, 16
	s_cmp_gt_i32 s1, s9
	s_cbranch_scc0 .Lcf_zero2
	s_add_i32 s10, s8, s1
	s_mul_i32 s10, s10, s86
	s_add_u32 s12, s18, s10
	s_addc_u32 s13, s19, 0
	s_add_u32 s12, s12, 0x6900600
	s_addc_u32 s13, s13, 0
	global_load_dwordx4 v[32:35], v0, s[12:13]
	global_load_dwordx4 v[36:39], v0, s[12:13] offset:1024
	s_branch .Lcf_next2
.Lcf_zero2:
	v_mov_b32_e32 v32, 0
	v_mov_b32_e32 v33, 0
	v_mov_b32_e32 v34, 0
	v_mov_b32_e32 v35, 0
	v_mov_b32_e32 v36, 0
	v_mov_b32_e32 v37, 0
	v_mov_b32_e32 v38, 0
	v_mov_b32_e32 v39, 0
.Lcf_next2:
	s_add_i32 s1, s0, 24
	s_cmp_gt_i32 s1, s9
	s_cbranch_scc0 .Lcf_zero3
	s_add_i32 s10, s8, s1
	s_mul_i32 s10, s10, s86
	s_add_u32 s20, s18, s10
	s_addc_u32 s21, s19, 0
	s_add_u32 s20, s20, 0x6900600
	s_addc_u32 s21, s21, 0
	global_load_dwordx4 v[40:43], v0, s[20:21]
	global_load_dwordx4 v[44:47], v0, s[20:21] offset:1024
	s_branch .Lcf_next3
.Lcf_zero3:
	v_mov_b32_e32 v40, 0
	v_mov_b32_e32 v41, 0
	v_mov_b32_e32 v42, 0
	v_mov_b32_e32 v43, 0
	v_mov_b32_e32 v44, 0
	v_mov_b32_e32 v45, 0
	v_mov_b32_e32 v46, 0
	v_mov_b32_e32 v47, 0
.Lcf_next3:
	s_add_i32 s1, s0, 32
	s_cmp_gt_i32 s1, s9
	s_cbranch_scc0 .Lcf_zero4
	s_add_i32 s10, s8, s1
	s_mul_i32 s10, s10, s86
	s_add_u32 s12, s18, s10
	s_addc_u32 s13, s19, 0
	s_add_u32 s12, s12, 0x6900600
	s_addc_u32 s13, s13, 0
	global_load_dwordx4 v[48:51], v0, s[12:13]
	global_load_dwordx4 v[52:55], v0, s[12:13] offset:1024
	s_branch .Lcf_next4
.Lcf_zero4:
	v_mov_b32_e32 v48, 0
	v_mov_b32_e32 v49, 0
	v_mov_b32_e32 v50, 0
	v_mov_b32_e32 v51, 0
	v_mov_b32_e32 v52, 0
	v_mov_b32_e32 v53, 0
	v_mov_b32_e32 v54, 0
	v_mov_b32_e32 v55, 0
.Lcf_next4:
	s_add_i32 s1, s0, 40
	s_cmp_gt_i32 s1, s9
	s_cbranch_scc0 .Lcf_zero5
	s_add_i32 s10, s8, s1
	s_mul_i32 s10, s10, s86
	s_add_u32 s20, s18, s10
	s_addc_u32 s21, s19, 0
	s_add_u32 s20, s20, 0x6900600
	s_addc_u32 s21, s21, 0
	global_load_dwordx4 v[56:59], v0, s[20:21]
	global_load_dwordx4 v[60:63], v0, s[20:21] offset:1024
	s_branch .Lcf_next5
.Lcf_zero5:
	v_mov_b32_e32 v56, 0
	v_mov_b32_e32 v57, 0
	v_mov_b32_e32 v58, 0
	v_mov_b32_e32 v59, 0
	v_mov_b32_e32 v60, 0
	v_mov_b32_e32 v61, 0
	v_mov_b32_e32 v62, 0
	v_mov_b32_e32 v63, 0
.Lcf_next5:
	s_add_i32 s1, s0, 48
	s_cmp_gt_i32 s1, s9
	s_cbranch_scc0 .Lcf_zero6
	s_add_i32 s10, s8, s1
	s_mul_i32 s10, s10, s86
	s_add_u32 s12, s18, s10
	s_addc_u32 s13, s19, 0
	s_add_u32 s12, s12, 0x6900600
	s_addc_u32 s13, s13, 0
	global_load_dwordx4 v[64:67], v0, s[12:13]
	global_load_dwordx4 v[68:71], v0, s[12:13] offset:1024
	s_branch .Lcf_next6
.Lcf_zero6:
	v_mov_b32_e32 v64, 0
	v_mov_b32_e32 v65, 0
	v_mov_b32_e32 v66, 0
	v_mov_b32_e32 v67, 0
	v_mov_b32_e32 v68, 0
	v_mov_b32_e32 v69, 0
	v_mov_b32_e32 v70, 0
	v_mov_b32_e32 v71, 0
.Lcf_next6:
	s_add_i32 s1, s0, 56
	s_cmp_gt_i32 s1, 61
	s_cbranch_scc1 .Lcf_lddone
	s_cmp_gt_i32 s1, s9
	s_cbranch_scc0 .Lcf_zero7
	s_add_i32 s10, s8, s1
	s_mul_i32 s10, s10, s86
	s_add_u32 s20, s18, s10
	s_addc_u32 s21, s19, 0
	s_add_u32 s20, s20, 0x6900600
	s_addc_u32 s21, s21, 0
	global_load_dwordx4 v[72:75], v0, s[20:21]
	global_load_dwordx4 v[76:79], v0, s[20:21] offset:1024
	s_branch .Lcf_next7
.Lcf_zero7:
	v_mov_b32_e32 v72, 0
	v_mov_b32_e32 v73, 0
	v_mov_b32_e32 v74, 0
	v_mov_b32_e32 v75, 0
	v_mov_b32_e32 v76, 0
	v_mov_b32_e32 v77, 0
	v_mov_b32_e32 v78, 0
	v_mov_b32_e32 v79, 0
; #define LAS __attribute__((address_space(3)))
; __device__ __forceinline__ float sigmoidf_(float x) { return __builtin_amdgcn_rcpf(1.0f + __builtin_amdgcn_exp2f(-x * LOG2E)); }
; __device__ __forceinline__ void conv_unit(const Ctx& C0, const Params& p, int l, int unit) {
;     ...
;             if (s >= 0) { const bf16* row = P + (size_t)(t0 - 30 + r) * PN + C_UB + cg8; const v4u a = *(const v4u*)row, g = *(const v4u*)(row + 512);
;                 u0[0] = bflo(a.x) * sigmoidf_(bflo(g.x)); u0[1] = bfhi(a.x) * sigmoidf_(bfhi(g.x)); u0[2] = bflo(a.y) * sigmoidf_(bflo(g.y)); u0[3] = bfhi(a.y) * sigmoidf_(bfhi(g.y));
;                 u1[0] = bflo(a.z) * sigmoidf_(bflo(g.z)); u1[1] = bfhi(a.z) * sigmoidf_(bfhi(g.z)); u1[2] = bflo(a.w) * sigmoidf_(bflo(g.w)); u1[3] = bfhi(a.w) * sigmoidf_(bfhi(g.w)); }
;             *(LAS f32x4*)(U + r * 512 + cg8) = u0; *(LAS f32x4*)(U + r * 512 + cg8 + 4) = u1;
.Lcf_next7:
.Lcf_lddone:
	s_waitcnt vmcnt(0)
	v_lshlrev_b32_e32 v80, 16, v20
	v_and_b32_e32 v81, 0xffff0000, v20
	v_lshlrev_b32_e32 v88, 16, v16
	v_and_b32_e32 v89, 0xffff0000, v16
	v_lshlrev_b32_e32 v82, 16, v21
	v_and_b32_e32 v83, 0xffff0000, v21
	v_lshlrev_b32_e32 v90, 16, v17
	v_and_b32_e32 v91, 0xffff0000, v17
	v_lshlrev_b32_e32 v84, 16, v22
	v_and_b32_e32 v85, 0xffff0000, v22
	v_lshlrev_b32_e32 v92, 16, v18
	v_and_b32_e32 v93, 0xffff0000, v18
	v_lshlrev_b32_e32 v86, 16, v23
	v_and_b32_e32 v87, 0xffff0000, v23
	v_lshlrev_b32_e32 v94, 16, v19
	v_and_b32_e32 v95, 0xffff0000, v19
	v_mul_f32_e32 v80, 0xbfb8aa3b, v80
	v_mul_f32_e32 v81, 0xbfb8aa3b, v81
	v_mul_f32_e32 v82, 0xbfb8aa3b, v82
	v_mul_f32_e32 v83, 0xbfb8aa3b, v83
	v_mul_f32_e32 v84, 0xbfb8aa3b, v84
	v_mul_f32_e32 v85, 0xbfb8aa3b, v85
	v_mul_f32_e32 v86, 0xbfb8aa3b, v86
	v_mul_f32_e32 v87, 0xbfb8aa3b, v87
	v_exp_f32_e32 v80, v80
	v_exp_f32_e32 v81, v81
	v_exp_f32_e32 v82, v82
	v_exp_f32_e32 v83, v83
	v_exp_f32_e32 v84, v84
	v_exp_f32_e32 v85, v85
	v_exp_f32_e32 v86, v86
	v_exp_f32_e32 v87, v87
	v_add_f32_e32 v80, 1.0, v80
	v_add_f32_e32 v81, 1.0, v81
	v_add_f32_e32 v82, 1.0, v82
	v_add_f32_e32 v83, 1.0, v83
	v_add_f32_e32 v84, 1.0, v84
	v_add_f32_e32 v85, 1.0, v85
	v_add_f32_e32 v86, 1.0, v86
	v_add_f32_e32 v87, 1.0, v87
	v_rcp_f32_e32 v80, v80
	v_rcp_f32_e32 v81, v81
	v_rcp_f32_e32 v82, v82
	v_rcp_f32_e32 v83, v83
	v_rcp_f32_e32 v84, v84
	v_rcp_f32_e32 v85, v85
	v_rcp_f32_e32 v86, v86
	v_rcp_f32_e32 v87, v87
	v_pk_mul_f32 v[88:89], v[88:89], v[80:81]
	v_pk_mul_f32 v[90:91], v[90:91], v[82:83]
	v_pk_mul_f32 v[92:93], v[92:93], v[84:85]
	v_pk_mul_f32 v[94:95], v[94:95], v[86:87]
	ds_write_b128 v14, v[88:91]
	ds_write_b128 v14, v[92:95] offset:16
	v_lshlrev_b32_e32 v80, 16, v28
	v_and_b32_e32 v81, 0xffff0000, v28
	v_lshlrev_b32_e32 v96, 16, v24
	v_and_b32_e32 v97, 0xffff0000, v24
	v_lshlrev_b32_e32 v82, 16, v29
	v_and_b32_e32 v83, 0xffff0000, v29
	v_lshlrev_b32_e32 v98, 16, v25
	v_and_b32_e32 v99, 0xffff0000, v25
	v_lshlrev_b32_e32 v84, 16, v30
	v_and_b32_e32 v85, 0xffff0000, v30
	v_lshlrev_b32_e32 v100, 16, v26
	v_and_b32_e32 v101, 0xffff0000, v26
	v_lshlrev_b32_e32 v86, 16, v31
	v_and_b32_e32 v87, 0xffff0000, v31
	v_lshlrev_b32_e32 v102, 16, v27
	v_and_b32_e32 v103, 0xffff0000, v27
	v_mul_f32_e32 v80, 0xbfb8aa3b, v80
	v_mul_f32_e32 v81, 0xbfb8aa3b, v81
	v_mul_f32_e32 v82, 0xbfb8aa3b, v82
	v_mul_f32_e32 v83, 0xbfb8aa3b, v83
	v_mul_f32_e32 v84, 0xbfb8aa3b, v84
	v_mul_f32_e32 v85, 0xbfb8aa3b, v85
	v_mul_f32_e32 v86, 0xbfb8aa3b, v86
	v_mul_f32_e32 v87, 0xbfb8aa3b, v87
	v_exp_f32_e32 v80, v80
	v_exp_f32_e32 v81, v81
	v_exp_f32_e32 v82, v82
	v_exp_f32_e32 v83, v83
	v_exp_f32_e32 v84, v84
	v_exp_f32_e32 v85, v85
	v_exp_f32_e32 v86, v86
	v_exp_f32_e32 v87, v87
	v_add_f32_e32 v80, 1.0, v80
	v_add_f32_e32 v81, 1.0, v81
	v_add_f32_e32 v82, 1.0, v82
	v_add_f32_e32 v83, 1.0, v83
	v_add_f32_e32 v84, 1.0, v84
	v_add_f32_e32 v85, 1.0, v85
	v_add_f32_e32 v86, 1.0, v86
	v_add_f32_e32 v87, 1.0, v87
	v_rcp_f32_e32 v80, v80
	v_rcp_f32_e32 v81, v81
	v_rcp_f32_e32 v82, v82
	v_rcp_f32_e32 v83, v83
	v_rcp_f32_e32 v84, v84
	v_rcp_f32_e32 v85, v85
	v_rcp_f32_e32 v86, v86
	v_rcp_f32_e32 v87, v87
	v_pk_mul_f32 v[96:97], v[96:97], v[80:81]
	v_pk_mul_f32 v[98:99], v[98:99], v[82:83]
	v_pk_mul_f32 v[100:101], v[100:101], v[84:85]
	v_pk_mul_f32 v[102:103], v[102:103], v[86:87]
	ds_write_b128 v14, v[96:99] offset:16384
	ds_write_b128 v14, v[100:103] offset:16400
	v_lshlrev_b32_e32 v80, 16, v36
	v_and_b32_e32 v81, 0xffff0000, v36
	v_lshlrev_b32_e32 v88, 16, v32
	v_and_b32_e32 v89, 0xffff0000, v32
	v_lshlrev_b32_e32 v82, 16, v37
	v_and_b32_e32 v83, 0xffff0000, v37
	v_lshlrev_b32_e32 v90, 16, v33
	v_and_b32_e32 v91, 0xffff0000, v33
	v_lshlrev_b32_e32 v84, 16, v38
	v_and_b32_e32 v85, 0xffff0000, v38
	v_lshlrev_b32_e32 v92, 16, v34
	v_and_b32_e32 v93, 0xffff0000, v34
	v_lshlrev_b32_e32 v86, 16, v39
	v_and_b32_e32 v87, 0xffff0000, v39
	v_lshlrev_b32_e32 v94, 16, v35
	v_and_b32_e32 v95, 0xffff0000, v35
	v_mul_f32_e32 v80, 0xbfb8aa3b, v80
	v_mul_f32_e32 v81, 0xbfb8aa3b, v81
	v_mul_f32_e32 v82, 0xbfb8aa3b, v82
	v_mul_f32_e32 v83, 0xbfb8aa3b, v83
	v_mul_f32_e32 v84, 0xbfb8aa3b, v84
	v_mul_f32_e32 v85, 0xbfb8aa3b, v85
	v_mul_f32_e32 v86, 0xbfb8aa3b, v86
	v_mul_f32_e32 v87, 0xbfb8aa3b, v87
	v_exp_f32_e32 v80, v80
	v_exp_f32_e32 v81, v81
	v_exp_f32_e32 v82, v82
	v_exp_f32_e32 v83, v83
	v_exp_f32_e32 v84, v84
	v_exp_f32_e32 v85, v85
	v_exp_f32_e32 v86, v86
	v_exp_f32_e32 v87, v87
	v_add_f32_e32 v80, 1.0, v80
	v_add_f32_e32 v81, 1.0, v81
	v_add_f32_e32 v82, 1.0, v82
	v_add_f32_e32 v83, 1.0, v83
	v_add_f32_e32 v84, 1.0, v84
	v_add_f32_e32 v85, 1.0, v85
	v_add_f32_e32 v86, 1.0, v86
	v_add_f32_e32 v87, 1.0, v87
	v_rcp_f32_e32 v80, v80
	v_rcp_f32_e32 v81, v81
	v_rcp_f32_e32 v82, v82
	v_rcp_f32_e32 v83, v83
	v_rcp_f32_e32 v84, v84
	v_rcp_f32_e32 v85, v85
	v_rcp_f32_e32 v86, v86
	v_rcp_f32_e32 v87, v87
	v_pk_mul_f32 v[88:89], v[88:89], v[80:81]
	v_pk_mul_f32 v[90:91], v[90:91], v[82:83]
	v_pk_mul_f32 v[92:93], v[92:93], v[84:85]
	v_pk_mul_f32 v[94:95], v[94:95], v[86:87]
	ds_write_b128 v14, v[88:91] offset:32768
	ds_write_b128 v14, v[92:95] offset:32784
	v_lshlrev_b32_e32 v80, 16, v44
	v_and_b32_e32 v81, 0xffff0000, v44
	v_lshlrev_b32_e32 v96, 16, v40
	v_and_b32_e32 v97, 0xffff0000, v40
	v_lshlrev_b32_e32 v82, 16, v45
	v_and_b32_e32 v83, 0xffff0000, v45
	v_lshlrev_b32_e32 v98, 16, v41
	v_and_b32_e32 v99, 0xffff0000, v41
	v_lshlrev_b32_e32 v84, 16, v46
	v_and_b32_e32 v85, 0xffff0000, v46
	v_lshlrev_b32_e32 v100, 16, v42
	v_and_b32_e32 v101, 0xffff0000, v42
	v_lshlrev_b32_e32 v86, 16, v47
	v_and_b32_e32 v87, 0xffff0000, v47
; #define LAS __attribute__((address_space(3)))
; __device__ __forceinline__ float sigmoidf_(float x) { return __builtin_amdgcn_rcpf(1.0f + __builtin_amdgcn_exp2f(-x * LOG2E)); }
; __device__ __forceinline__ void conv_unit(const Ctx& C0, const Params& p, int l, int unit) {
;     ...
;             if (s >= 0) { const bf16* row = P + (size_t)(t0 - 30 + r) * PN + C_UB + cg8; const v4u a = *(const v4u*)row, g = *(const v4u*)(row + 512);
;                 u0[0] = bflo(a.x) * sigmoidf_(bflo(g.x)); u0[1] = bfhi(a.x) * sigmoidf_(bfhi(g.x)); u0[2] = bflo(a.y) * sigmoidf_(bflo(g.y)); u0[3] = bfhi(a.y) * sigmoidf_(bfhi(g.y));
;                 u1[0] = bflo(a.z) * sigmoidf_(bflo(g.z)); u1[1] = bfhi(a.z) * sigmoidf_(bfhi(g.z)); u1[2] = bflo(a.w) * sigmoidf_(bflo(g.w)); u1[3] = bfhi(a.w) * sigmoidf_(bfhi(g.w)); }
;             *(LAS f32x4*)(U + r * 512 + cg8) = u0; *(LAS f32x4*)(U + r * 512 + cg8 + 4) = u1;
	v_lshlrev_b32_e32 v102, 16, v43
	v_and_b32_e32 v103, 0xffff0000, v43
	v_mul_f32_e32 v80, 0xbfb8aa3b, v80
	v_mul_f32_e32 v81, 0xbfb8aa3b, v81
	v_mul_f32_e32 v82, 0xbfb8aa3b, v82
	v_mul_f32_e32 v83, 0xbfb8aa3b, v83
	v_mul_f32_e32 v84, 0xbfb8aa3b, v84
	v_mul_f32_e32 v85, 0xbfb8aa3b, v85
	v_mul_f32_e32 v86, 0xbfb8aa3b, v86
	v_mul_f32_e32 v87, 0xbfb8aa3b, v87
	v_exp_f32_e32 v80, v80
	v_exp_f32_e32 v81, v81
	v_exp_f32_e32 v82, v82
	v_exp_f32_e32 v83, v83
	v_exp_f32_e32 v84, v84
	v_exp_f32_e32 v85, v85
	v_exp_f32_e32 v86, v86
	v_exp_f32_e32 v87, v87
	v_add_f32_e32 v80, 1.0, v80
	v_add_f32_e32 v81, 1.0, v81
	v_add_f32_e32 v82, 1.0, v82
	v_add_f32_e32 v83, 1.0, v83
	v_add_f32_e32 v84, 1.0, v84
	v_add_f32_e32 v85, 1.0, v85
	v_add_f32_e32 v86, 1.0, v86
	v_add_f32_e32 v87, 1.0, v87
	v_rcp_f32_e32 v80, v80
	v_rcp_f32_e32 v81, v81
	v_rcp_f32_e32 v82, v82
	v_rcp_f32_e32 v83, v83
	v_rcp_f32_e32 v84, v84
	v_rcp_f32_e32 v85, v85
	v_rcp_f32_e32 v86, v86
	v_rcp_f32_e32 v87, v87
	v_pk_mul_f32 v[96:97], v[96:97], v[80:81]
	v_pk_mul_f32 v[98:99], v[98:99], v[82:83]
	v_pk_mul_f32 v[100:101], v[100:101], v[84:85]
	v_pk_mul_f32 v[102:103], v[102:103], v[86:87]
	ds_write_b128 v14, v[96:99] offset:49152
	ds_write_b128 v14, v[100:103] offset:49168
	v_lshlrev_b32_e32 v80, 16, v52
	v_and_b32_e32 v81, 0xffff0000, v52
	v_lshlrev_b32_e32 v88, 16, v48
	v_and_b32_e32 v89, 0xffff0000, v48
	v_lshlrev_b32_e32 v82, 16, v53
	v_and_b32_e32 v83, 0xffff0000, v53
	v_lshlrev_b32_e32 v90, 16, v49
	v_and_b32_e32 v91, 0xffff0000, v49
	v_lshlrev_b32_e32 v84, 16, v54
	v_and_b32_e32 v85, 0xffff0000, v54
	v_lshlrev_b32_e32 v92, 16, v50
	v_and_b32_e32 v93, 0xffff0000, v50
	v_lshlrev_b32_e32 v86, 16, v55
	v_and_b32_e32 v87, 0xffff0000, v55
	v_lshlrev_b32_e32 v94, 16, v51
	v_and_b32_e32 v95, 0xffff0000, v51
	v_mul_f32_e32 v80, 0xbfb8aa3b, v80
	v_mul_f32_e32 v81, 0xbfb8aa3b, v81
	v_mul_f32_e32 v82, 0xbfb8aa3b, v82
	v_mul_f32_e32 v83, 0xbfb8aa3b, v83
	v_mul_f32_e32 v84, 0xbfb8aa3b, v84
	v_mul_f32_e32 v85, 0xbfb8aa3b, v85
	v_mul_f32_e32 v86, 0xbfb8aa3b, v86
	v_mul_f32_e32 v87, 0xbfb8aa3b, v87
	v_exp_f32_e32 v80, v80
	v_exp_f32_e32 v81, v81
	v_exp_f32_e32 v82, v82
	v_exp_f32_e32 v83, v83
	v_exp_f32_e32 v84, v84
	v_exp_f32_e32 v85, v85
	v_exp_f32_e32 v86, v86
	v_exp_f32_e32 v87, v87
	v_add_f32_e32 v80, 1.0, v80
	v_add_f32_e32 v81, 1.0, v81
	v_add_f32_e32 v82, 1.0, v82
	v_add_f32_e32 v83, 1.0, v83
	v_add_f32_e32 v84, 1.0, v84
	v_add_f32_e32 v85, 1.0, v85
	v_add_f32_e32 v86, 1.0, v86
	v_add_f32_e32 v87, 1.0, v87
	v_rcp_f32_e32 v80, v80
	v_rcp_f32_e32 v81, v81
	v_rcp_f32_e32 v82, v82
	v_rcp_f32_e32 v83, v83
	v_rcp_f32_e32 v84, v84
	v_rcp_f32_e32 v85, v85
	v_rcp_f32_e32 v86, v86
	v_rcp_f32_e32 v87, v87
	v_pk_mul_f32 v[88:89], v[88:89], v[80:81]
	v_pk_mul_f32 v[90:91], v[90:91], v[82:83]
	v_pk_mul_f32 v[92:93], v[92:93], v[84:85]
	v_pk_mul_f32 v[94:95], v[94:95], v[86:87]
	ds_write_b128 v15, v[88:91]
	ds_write_b128 v15, v[92:95] offset:16
	v_lshlrev_b32_e32 v80, 16, v60
	v_and_b32_e32 v81, 0xffff0000, v60
	v_lshlrev_b32_e32 v96, 16, v56
	v_and_b32_e32 v97, 0xffff0000, v56
	v_lshlrev_b32_e32 v82, 16, v61
	v_and_b32_e32 v83, 0xffff0000, v61
	v_lshlrev_b32_e32 v98, 16, v57
	v_and_b32_e32 v99, 0xffff0000, v57
	v_lshlrev_b32_e32 v84, 16, v62
	v_and_b32_e32 v85, 0xffff0000, v62
	v_lshlrev_b32_e32 v100, 16, v58
	v_and_b32_e32 v101, 0xffff0000, v58
	v_lshlrev_b32_e32 v86, 16, v63
	v_and_b32_e32 v87, 0xffff0000, v63
	v_lshlrev_b32_e32 v102, 16, v59
	v_and_b32_e32 v103, 0xffff0000, v59
	v_mul_f32_e32 v80, 0xbfb8aa3b, v80
	v_mul_f32_e32 v81, 0xbfb8aa3b, v81
	v_mul_f32_e32 v82, 0xbfb8aa3b, v82
	v_mul_f32_e32 v83, 0xbfb8aa3b, v83
	v_mul_f32_e32 v84, 0xbfb8aa3b, v84
	v_mul_f32_e32 v85, 0xbfb8aa3b, v85
	v_mul_f32_e32 v86, 0xbfb8aa3b, v86
	v_mul_f32_e32 v87, 0xbfb8aa3b, v87
	v_exp_f32_e32 v80, v80
	v_exp_f32_e32 v81, v81
	v_exp_f32_e32 v82, v82
	v_exp_f32_e32 v83, v83
	v_exp_f32_e32 v84, v84
	v_exp_f32_e32 v85, v85
	v_exp_f32_e32 v86, v86
	v_exp_f32_e32 v87, v87
	v_add_f32_e32 v80, 1.0, v80
	v_add_f32_e32 v81, 1.0, v81
	v_add_f32_e32 v82, 1.0, v82
	v_add_f32_e32 v83, 1.0, v83
	v_add_f32_e32 v84, 1.0, v84
	v_add_f32_e32 v85, 1.0, v85
	v_add_f32_e32 v86, 1.0, v86
	v_add_f32_e32 v87, 1.0, v87
	v_rcp_f32_e32 v80, v80
	v_rcp_f32_e32 v81, v81
	v_rcp_f32_e32 v82, v82
	v_rcp_f32_e32 v83, v83
	v_rcp_f32_e32 v84, v84
	v_rcp_f32_e32 v85, v85
	v_rcp_f32_e32 v86, v86
	v_rcp_f32_e32 v87, v87
	v_pk_mul_f32 v[96:97], v[96:97], v[80:81]
	v_pk_mul_f32 v[98:99], v[98:99], v[82:83]
	v_pk_mul_f32 v[100:101], v[100:101], v[84:85]
	v_pk_mul_f32 v[102:103], v[102:103], v[86:87]
	ds_write_b128 v15, v[96:99] offset:16384
	ds_write_b128 v15, v[100:103] offset:16400
	v_lshlrev_b32_e32 v80, 16, v68
	v_and_b32_e32 v81, 0xffff0000, v68
	v_lshlrev_b32_e32 v88, 16, v64
	v_and_b32_e32 v89, 0xffff0000, v64
	v_lshlrev_b32_e32 v82, 16, v69
	v_and_b32_e32 v83, 0xffff0000, v69
	v_lshlrev_b32_e32 v90, 16, v65
	v_and_b32_e32 v91, 0xffff0000, v65
	v_lshlrev_b32_e32 v84, 16, v70
	v_and_b32_e32 v85, 0xffff0000, v70
	v_lshlrev_b32_e32 v92, 16, v66
	v_and_b32_e32 v93, 0xffff0000, v66
	v_lshlrev_b32_e32 v86, 16, v71
	v_and_b32_e32 v87, 0xffff0000, v71
	v_lshlrev_b32_e32 v94, 16, v67
	v_and_b32_e32 v95, 0xffff0000, v67
	v_mul_f32_e32 v80, 0xbfb8aa3b, v80
	v_mul_f32_e32 v81, 0xbfb8aa3b, v81
	v_mul_f32_e32 v82, 0xbfb8aa3b, v82
	v_mul_f32_e32 v83, 0xbfb8aa3b, v83
	v_mul_f32_e32 v84, 0xbfb8aa3b, v84
	v_mul_f32_e32 v85, 0xbfb8aa3b, v85
	v_mul_f32_e32 v86, 0xbfb8aa3b, v86
	v_mul_f32_e32 v87, 0xbfb8aa3b, v87
	v_exp_f32_e32 v80, v80
	v_exp_f32_e32 v81, v81
	v_exp_f32_e32 v82, v82
	v_exp_f32_e32 v83, v83
	v_exp_f32_e32 v84, v84
	v_exp_f32_e32 v85, v85
	v_exp_f32_e32 v86, v86
	v_exp_f32_e32 v87, v87
	v_add_f32_e32 v80, 1.0, v80
	v_add_f32_e32 v81, 1.0, v81
	v_add_f32_e32 v82, 1.0, v82
	v_add_f32_e32 v83, 1.0, v83
	v_add_f32_e32 v84, 1.0, v84
	v_add_f32_e32 v85, 1.0, v85
	v_add_f32_e32 v86, 1.0, v86
	v_add_f32_e32 v87, 1.0, v87
	v_rcp_f32_e32 v80, v80
	v_rcp_f32_e32 v81, v81
	v_rcp_f32_e32 v82, v82
	v_rcp_f32_e32 v83, v83
	v_rcp_f32_e32 v84, v84
	v_rcp_f32_e32 v85, v85
	v_rcp_f32_e32 v86, v86
	v_rcp_f32_e32 v87, v87
	v_pk_mul_f32 v[88:89], v[88:89], v[80:81]
	v_pk_mul_f32 v[90:91], v[90:91], v[82:83]
	v_pk_mul_f32 v[92:93], v[92:93], v[84:85]
	v_pk_mul_f32 v[94:95], v[94:95], v[86:87]
	ds_write_b128 v15, v[88:91] offset:32768
	ds_write_b128 v15, v[92:95] offset:32784
	s_add_i32 s1, s0, 56
	s_cmp_gt_i32 s1, 61
	s_cbranch_scc1 .Lcf_done
; #define LAS __attribute__((address_space(3)))
; __device__ __forceinline__ float sigmoidf_(float x) { return __builtin_amdgcn_rcpf(1.0f + __builtin_amdgcn_exp2f(-x * LOG2E)); }
; __device__ __forceinline__ void conv_unit(const Ctx& C0, const Params& p, int l, int unit) {
;     ...
;             if (s >= 0) { const bf16* row = P + (size_t)(t0 - 30 + r) * PN + C_UB + cg8; const v4u a = *(const v4u*)row, g = *(const v4u*)(row + 512);
;                 u0[0] = bflo(a.x) * sigmoidf_(bflo(g.x)); u0[1] = bfhi(a.x) * sigmoidf_(bfhi(g.x)); u0[2] = bflo(a.y) * sigmoidf_(bflo(g.y)); u0[3] = bfhi(a.y) * sigmoidf_(bfhi(g.y));
;                 u1[0] = bflo(a.z) * sigmoidf_(bflo(g.z)); u1[1] = bfhi(a.z) * sigmoidf_(bfhi(g.z)); u1[2] = bflo(a.w) * sigmoidf_(bflo(g.w)); u1[3] = bfhi(a.w) * sigmoidf_(bfhi(g.w)); }
;             *(LAS f32x4*)(U + r * 512 + cg8) = u0; *(LAS f32x4*)(U + r * 512 + cg8 + 4) = u1;
	v_lshlrev_b32_e32 v80, 16, v76
	v_and_b32_e32 v81, 0xffff0000, v76
	v_lshlrev_b32_e32 v96, 16, v72
	v_and_b32_e32 v97, 0xffff0000, v72
	v_lshlrev_b32_e32 v82, 16, v77
	v_and_b32_e32 v83, 0xffff0000, v77
	v_lshlrev_b32_e32 v98, 16, v73
	v_and_b32_e32 v99, 0xffff0000, v73
	v_lshlrev_b32_e32 v84, 16, v78
	v_and_b32_e32 v85, 0xffff0000, v78
	v_lshlrev_b32_e32 v100, 16, v74
	v_and_b32_e32 v101, 0xffff0000, v74
	v_lshlrev_b32_e32 v86, 16, v79
	v_and_b32_e32 v87, 0xffff0000, v79
	v_lshlrev_b32_e32 v102, 16, v75
	v_and_b32_e32 v103, 0xffff0000, v75
	v_mul_f32_e32 v80, 0xbfb8aa3b, v80
	v_mul_f32_e32 v81, 0xbfb8aa3b, v81
	v_mul_f32_e32 v82, 0xbfb8aa3b, v82
	v_mul_f32_e32 v83, 0xbfb8aa3b, v83
	v_mul_f32_e32 v84, 0xbfb8aa3b, v84
	v_mul_f32_e32 v85, 0xbfb8aa3b, v85
	v_mul_f32_e32 v86, 0xbfb8aa3b, v86
	v_mul_f32_e32 v87, 0xbfb8aa3b, v87
	v_exp_f32_e32 v80, v80
	v_exp_f32_e32 v81, v81
	v_exp_f32_e32 v82, v82
	v_exp_f32_e32 v83, v83
	v_exp_f32_e32 v84, v84
	v_exp_f32_e32 v85, v85
	v_exp_f32_e32 v86, v86
	v_exp_f32_e32 v87, v87
	v_add_f32_e32 v80, 1.0, v80
	v_add_f32_e32 v81, 1.0, v81
	v_add_f32_e32 v82, 1.0, v82
	v_add_f32_e32 v83, 1.0, v83
	v_add_f32_e32 v84, 1.0, v84
	v_add_f32_e32 v85, 1.0, v85
	v_add_f32_e32 v86, 1.0, v86
	v_add_f32_e32 v87, 1.0, v87
	v_rcp_f32_e32 v80, v80
	v_rcp_f32_e32 v81, v81
	v_rcp_f32_e32 v82, v82
	v_rcp_f32_e32 v83, v83
	v_rcp_f32_e32 v84, v84
	v_rcp_f32_e32 v85, v85
	v_rcp_f32_e32 v86, v86
	v_rcp_f32_e32 v87, v87
	v_pk_mul_f32 v[96:97], v[96:97], v[80:81]
	v_pk_mul_f32 v[98:99], v[98:99], v[82:83]
	v_pk_mul_f32 v[100:101], v[100:101], v[84:85]
	v_pk_mul_f32 v[102:103], v[102:103], v[86:87]
	ds_write_b128 v15, v[96:99] offset:49152
	ds_write_b128 v15, v[100:103] offset:49168
; __device__ __forceinline__ void conv_unit(const Ctx& C0, const Params& p, int l, int unit) {
;     ...
;     __syncthreads();
;     float w[31];
; #pragma unroll
;     for (int j = 0; j < 31; ++j) w[j] = p.w_dw[(size_t)l * 31 * 512 + j * 512 + c];
;     const float bias = p.b_dw[l * 512 + c];
.Lcf_done:
	v_ashrrev_i32_e32 v11, 31, v10
	s_waitcnt vmcnt(6)
	v_lshl_add_u64 v[4:5], v[10:11], 2, s[38:39]
	v_add_co_u32_e32 v64, vcc, 0xf000, v4
	s_mov_b32 s0, 0xe000
	s_nop 0
	v_addc_co_u32_e32 v65, vcc, 0, v5, vcc
	v_add_co_u32_e32 v62, vcc, s0, v4
	s_mov_b32 s0, 0xc000
	s_nop 0
	v_addc_co_u32_e32 v63, vcc, 0, v5, vcc
	v_add_co_u32_e32 v58, vcc, 0xd000, v4
	v_add_u32_e32 v2, s88, v10
	s_nop 0
	v_addc_co_u32_e32 v59, vcc, 0, v5, vcc
	v_add_co_u32_e32 v54, vcc, s0, v4
	s_mov_b32 s0, 0xa000
	s_nop 0
	v_addc_co_u32_e32 v55, vcc, 0, v5, vcc
	v_add_co_u32_e32 v50, vcc, 0xb000, v4
	v_readlane_b32 s44, v251, 12
	s_nop 0
	v_addc_co_u32_e32 v51, vcc, 0, v5, vcc
	v_add_co_u32_e32 v46, vcc, s0, v4
	s_mov_b32 s0, 0x8000
	s_nop 0
	v_addc_co_u32_e32 v47, vcc, 0, v5, vcc
	v_add_co_u32_e32 v42, vcc, 0x9000, v4
	v_ashrrev_i32_e32 v3, 31, v2
	s_nop 0
	v_addc_co_u32_e32 v43, vcc, 0, v5, vcc
	s_waitcnt vmcnt(3)
	v_add_co_u32_e32 v38, vcc, s0, v4
	s_movk_i32 s0, 0x6000
	s_waitcnt vmcnt(2)
	v_addc_co_u32_e32 v39, vcc, 0, v5, vcc
	v_add_co_u32_e32 v34, vcc, 0x7000, v4
	v_readlane_b32 s52, v251, 20
	s_nop 0
	v_addc_co_u32_e32 v35, vcc, 0, v5, vcc
	v_add_co_u32_e32 v30, vcc, s0, v4
	s_movk_i32 s0, 0x4000
	s_nop 0
	v_addc_co_u32_e32 v31, vcc, 0, v5, vcc
	v_add_co_u32_e32 v26, vcc, 0x5000, v4
	v_readlane_b32 s53, v251, 21
	s_nop 0
	v_addc_co_u32_e32 v27, vcc, 0, v5, vcc
	v_add_co_u32_e32 v22, vcc, s0, v4
	s_movk_i32 s0, 0x3000
	s_nop 0
	v_addc_co_u32_e32 v23, vcc, 0, v5, vcc
	v_add_co_u32_e32 v18, vcc, s0, v4
	s_movk_i32 s0, 0x2000
	s_nop 0
	v_addc_co_u32_e32 v19, vcc, 0, v5, vcc
	v_add_co_u32_e32 v14, vcc, s0, v4
	s_movk_i32 s0, 0x1000
	s_nop 0
	v_addc_co_u32_e32 v15, vcc, 0, v5, vcc
	v_lshl_add_u64 v[66:67], v[2:3], 2, s[52:53]
	v_add_co_u32_e32 v8, vcc, s0, v4
	s_waitcnt lgkmcnt(0)
	s_barrier
	v_addc_co_u32_e32 v9, vcc, 0, v5, vcc
	global_load_dword v2, v[4:5], off
	s_nop 0
	global_load_dword v4, v[4:5], off offset:2048
	s_nop 0
	global_load_dword v6, v[8:9], off
	s_nop 0
	global_load_dword v8, v[8:9], off offset:2048
	s_nop 0
	global_load_dword v12, v[14:15], off
	s_nop 0
	global_load_dword v14, v[14:15], off offset:2048
	s_nop 0
	global_load_dword v16, v[18:19], off
	s_nop 0
	global_load_dword v18, v[18:19], off offset:2048
	s_nop 0
	global_load_dword v20, v[22:23], off
	s_nop 0
	global_load_dword v22, v[22:23], off offset:2048
	s_nop 0
	global_load_dword v24, v[26:27], off
	s_nop 0
	global_load_dword v26, v[26:27], off offset:2048
	s_nop 0
	global_load_dword v28, v[30:31], off
	s_nop 0
	global_load_dword v30, v[30:31], off offset:2048
	s_nop 0
	global_load_dword v32, v[34:35], off
	s_nop 0
	global_load_dword v34, v[34:35], off offset:2048
	s_nop 0
	global_load_dword v36, v[38:39], off
	s_nop 0
	global_load_dword v38, v[38:39], off offset:2048
	s_nop 0
	global_load_dword v40, v[42:43], off
	s_nop 0
	global_load_dword v42, v[42:43], off offset:2048
	s_nop 0
	global_load_dword v44, v[46:47], off
	s_nop 0
	global_load_dword v46, v[46:47], off offset:2048
	s_nop 0
	global_load_dword v48, v[50:51], off
	s_nop 0
	global_load_dword v50, v[50:51], off offset:2048
	s_nop 0
	global_load_dword v52, v[54:55], off
	s_nop 0
	global_load_dword v54, v[54:55], off offset:2048
	s_nop 0
	global_load_dword v56, v[58:59], off
	s_nop 0
	global_load_dword v58, v[58:59], off offset:2048
	s_nop 0
	global_load_dword v60, v[62:63], off
	s_nop 0
	global_load_dword v62, v[62:63], off offset:2048
	s_nop 0
	global_load_dword v64, v[64:65], off
	s_nop 0
	global_load_dword v66, v[66:67], off
	v_lshl_add_u32 v0, v10, 2, 0
	s_mov_b32 s0, 0
	s_mov_b32 s1, 8
	s_mov_b32 s8, 4
	v_readlane_b32 s45, v251, 13
	v_readlane_b32 s46, v251, 14
	v_readlane_b32 s47, v251, 15
	v_readlane_b32 s48, v251, 16
	v_readlane_b32 s49, v251, 17
	v_readlane_b32 s50, v251, 18
	v_readlane_b32 s51, v251, 19
	v_readlane_b32 s54, v251, 22
	v_readlane_b32 s55, v251, 23
	v_readlane_b32 s56, v251, 24
	v_readlane_b32 s57, v251, 25
	v_readlane_b32 s58, v251, 26
	v_readlane_b32 s59, v251, 27
	s_waitcnt vmcnt(31)
	v_mov_b32_e32 v3, v2
	s_waitcnt vmcnt(30)
	v_mov_b32_e32 v5, v4
	s_waitcnt vmcnt(29)
	v_mov_b32_e32 v7, v6
	s_waitcnt vmcnt(28)
	v_mov_b32_e32 v9, v8
	s_waitcnt vmcnt(27)
	v_mov_b32_e32 v13, v12
	s_waitcnt vmcnt(26)
	v_mov_b32_e32 v15, v14
	s_waitcnt vmcnt(25)
	v_mov_b32_e32 v17, v16
	s_waitcnt vmcnt(24)
	v_mov_b32_e32 v19, v18
	s_waitcnt vmcnt(23)
	v_mov_b32_e32 v21, v20
	s_waitcnt vmcnt(22)
	v_mov_b32_e32 v23, v22
	s_waitcnt vmcnt(21)
	v_mov_b32_e32 v25, v24
	s_waitcnt vmcnt(20)
	v_mov_b32_e32 v27, v26
	s_waitcnt vmcnt(19)
	v_mov_b32_e32 v29, v28
	s_waitcnt vmcnt(18)
	v_mov_b32_e32 v31, v30
	s_waitcnt vmcnt(17)
	v_mov_b32_e32 v33, v32
	s_waitcnt vmcnt(16)
	v_mov_b32_e32 v35, v34
	s_waitcnt vmcnt(15)
	v_mov_b32_e32 v37, v36
	s_waitcnt vmcnt(14)
	v_mov_b32_e32 v39, v38
	s_waitcnt vmcnt(13)
	v_mov_b32_e32 v41, v40
	s_waitcnt vmcnt(12)
	v_mov_b32_e32 v43, v42
	s_waitcnt vmcnt(11)
	v_mov_b32_e32 v45, v44
	s_waitcnt vmcnt(10)
	v_mov_b32_e32 v47, v46
	s_waitcnt vmcnt(9)
	v_mov_b32_e32 v49, v48
	s_waitcnt vmcnt(8)
	v_mov_b32_e32 v51, v50
	s_waitcnt vmcnt(7)
	v_mov_b32_e32 v53, v52
	s_waitcnt vmcnt(6)
	v_mov_b32_e32 v55, v54
	s_waitcnt vmcnt(5)
	v_mov_b32_e32 v57, v56
	s_waitcnt vmcnt(4)
	v_mov_b32_e32 v59, v58
	s_waitcnt vmcnt(3)
	v_mov_b32_e32 v61, v60
	s_waitcnt vmcnt(2)
	v_mov_b32_e32 v63, v62
	s_waitcnt vmcnt(1)
	v_mov_b32_e32 v65, v64
	s_waitcnt vmcnt(0)
	v_mov_b32_e32 v67, v66
